# FF-IN K-loop: SP1 segment's two LDS-DMA loads moved to the head of the next SP2 segment (0/8 split), SP1 waits vmcnt(6)
# baseline (speedup 1.0000x reference)
; #define PG8_STAGE(bufoff, gbase, voff) do { _Pragma("unroll") for (int _i = 0; _i < 2; ++_i) \
;         __builtin_amdgcn_global_load_lds((const unsigned*)((const char*)(gbase) + (voff)[_i]), (PG8_LAS unsigned*)(lds + (bufoff) + ldsw + _i * 8192), 16, 0, 0); } while (0)
; #define PG8_LDA(dst, b, h) do { _Pragma("unroll") for (int m = 0; m < 4; ++m) _Pragma("unroll") for (int k = 0; k < 2; ++k) dst[m][k] = *(const PG8_LAS bf16x8*)(lds + PG8_SA(b, h) + aoff + m * 2048 + k * 1024); } while (0)
; #define PG8_LDB(dst, b, h) do { _Pragma("unroll") for (int n = 0; n < 2; ++n) _Pragma("unroll") for (int k = 0; k < 2; ++k) dst[n][k] = *(const PG8_LAS bf16x8*)(lds + PG8_SB(b, h) + boff + n * 2048 + k * 1024); } while (0)
; #define PG8_MMA(ai, bj, At, Bt) do { __builtin_amdgcn_s_setprio(1); _Pragma("unroll") for (int m = 0; m < 4; ++m) _Pragma("unroll") for (int n = 0; n < 2; ++n) _Pragma("unroll") for (int k = 0; k < 2; ++k) \
;         acc[ai][bj][m][n] = __builtin_amdgcn_mfma_f32_16x16x32_bf16(Bt[n][k], At[m][k], acc[ai][bj][m][n], 0, 0, 0); __builtin_amdgcn_s_setprio(0); } while (0)
; #define PG8_WAIT_V(n) asm volatile("s_waitcnt vmcnt(" #n ")" ::: "memory")
; #define PG8_WAIT_L(n) asm volatile("s_waitcnt lgkmcnt(" #n ")" ::: "memory")
; #define PG8_BAR __builtin_amdgcn_s_barrier()
; #define PG8_SCHED __builtin_amdgcn_sched_barrier(0)
; template <class Epi, class Sched, bool ALIGN_EPI = false, bool SP2 = false>
; __device__ __forceinline__ void gemm_phase(PG8_LAS unsigned char* lds, const Gemm g, const Sched& S, const Epi& E) {
;     ...
;             PG8_LDB(B0, 0, 0); PG8_LDB(B1, 0, 1); PG8_SCHED; PG8_LDA(At, 0, 0); PG8_STAGE(PG8_SA(1, 1), a1 + hstep, voffA);
;             PG8_WAIT_V(8); PG8_WAIT_L(0); PG8_BAR; PG8_MMA(0, 0, At, B0); PG8_MMA(0, 1, At, B1); PG8_BAR; PG8_SCHED;
;             PG8_LDA(At, 0, 1); PG8_STAGE(PG8_SB(0, 0), b2, voffB); PG8_STAGE(PG8_SB(0, 1), b2 + hstep, voffB); PG8_STAGE(PG8_SA(0, 0), a2, voffA);
;             PG8_WAIT_V(8); PG8_WAIT_L(0); PG8_BAR; PG8_MMA(1, 0, At, B0); PG8_MMA(1, 1, At, B1); PG8_BAR; PG8_SCHED;
.Lffin_nopf:
	v_add_u32_e32 v118, s69, v229
	v_add_u32_e32 v134, s72, v229
	ds_read_b128 v[106:109], v118
	ds_read_b128 v[110:113], v118 offset:1024
	ds_read_b128 v[114:117], v118 offset:2048
	ds_read_b128 v[118:121], v118 offset:3072
	ds_read_b128 v[122:125], v134
	ds_read_b128 v[126:129], v134 offset:1024
	ds_read_b128 v[130:133], v134 offset:2048
	ds_read_b128 v[134:137], v134 offset:3072
	ds_read_b128 v[162:165], v230
	ds_read_b128 v[166:169], v230 offset:1024
	ds_read_b128 v[170:173], v230 offset:2048
	ds_read_b128 v[192:195], v230 offset:3072
	ds_read_b128 v[196:199], v230 offset:4096
	ds_read_b128 v[200:203], v230 offset:5120
	ds_read_b128 v[204:207], v230 offset:6144
	ds_read_b128 v[208:211], v230 offset:7168
	s_waitcnt vmcnt(6)
	s_waitcnt lgkmcnt(0)
	s_barrier
	s_setprio 1
	s_waitcnt lgkmcnt(0)
	v_mfma_f32_16x16x32_bf16 v[158:161], v[106:109], v[162:165], v[158:161]
	v_mfma_f32_16x16x32_bf16 v[154:157], v[114:117], v[162:165], v[154:157]
	v_mfma_f32_16x16x32_bf16 v[142:145], v[106:109], v[170:173], v[142:145]
	v_mfma_f32_16x16x32_bf16 v[138:141], v[114:117], v[170:173], v[138:141]
	v_mfma_f32_16x16x32_bf16 v[94:97], v[106:109], v[196:199], v[94:97]
	v_mfma_f32_16x16x32_bf16 v[90:93], v[114:117], v[196:199], v[90:93]
	v_mfma_f32_16x16x32_bf16 v[78:81], v[106:109], v[204:207], v[78:81]
	v_mfma_f32_16x16x32_bf16 v[74:77], v[114:117], v[204:207], v[74:77]
	v_mfma_f32_16x16x32_bf16 v[158:161], v[110:113], v[166:169], v[158:161]
	v_mfma_f32_16x16x32_bf16 v[154:157], v[118:121], v[166:169], v[154:157]
	v_mfma_f32_16x16x32_bf16 v[142:145], v[110:113], v[192:195], v[142:145]
	v_mfma_f32_16x16x32_bf16 v[138:141], v[118:121], v[192:195], v[138:141]
	v_mfma_f32_16x16x32_bf16 v[94:97], v[110:113], v[200:203], v[94:97]
	v_mfma_f32_16x16x32_bf16 v[90:93], v[118:121], v[200:203], v[90:93]
	v_mfma_f32_16x16x32_bf16 v[78:81], v[110:113], v[208:211], v[78:81]
	v_mfma_f32_16x16x32_bf16 v[74:77], v[118:121], v[208:211], v[74:77]
	s_setprio 0
	s_setprio 1
	v_mfma_f32_16x16x32_bf16 v[150:153], v[122:125], v[162:165], v[150:153]
	v_mfma_f32_16x16x32_bf16 v[146:149], v[130:133], v[162:165], v[146:149]
	v_mfma_f32_16x16x32_bf16 v[102:105], v[122:125], v[170:173], v[102:105]
	v_mfma_f32_16x16x32_bf16 v[98:101], v[130:133], v[170:173], v[98:101]
	v_mfma_f32_16x16x32_bf16 v[86:89], v[122:125], v[196:199], v[86:89]
	v_mfma_f32_16x16x32_bf16 v[82:85], v[130:133], v[196:199], v[82:85]
	v_mfma_f32_16x16x32_bf16 v[70:73], v[122:125], v[204:207], v[70:73]
	v_mfma_f32_16x16x32_bf16 v[66:69], v[130:133], v[204:207], v[66:69]
	v_mfma_f32_16x16x32_bf16 v[150:153], v[126:129], v[166:169], v[150:153]
	v_mfma_f32_16x16x32_bf16 v[146:149], v[134:137], v[166:169], v[146:149]
	v_mfma_f32_16x16x32_bf16 v[102:105], v[126:129], v[192:195], v[102:105]
	v_mfma_f32_16x16x32_bf16 v[98:101], v[134:137], v[192:195], v[98:101]
	v_mfma_f32_16x16x32_bf16 v[86:89], v[126:129], v[200:203], v[86:89]
	v_mfma_f32_16x16x32_bf16 v[82:85], v[134:137], v[200:203], v[82:85]
	v_mfma_f32_16x16x32_bf16 v[70:73], v[126:129], v[208:211], v[70:73]
	v_mfma_f32_16x16x32_bf16 v[66:69], v[134:137], v[208:211], v[66:69]
	s_setprio 0
	s_barrier
	v_lshl_add_u64 v[212:213], s[8:9], 0, v[188:189]
	s_add_i32 m0, s53, 0xc000
	s_nop 0
	global_load_lds_dwordx4 v[212:213], off
	v_lshl_add_u64 v[212:213], s[8:9], 0, v[190:191]
	s_add_i32 m0, s53, 0xe000
	s_nop 0
	global_load_lds_dwordx4 v[212:213], off
	s_add_i32 s69, s69, s52
	v_lshl_add_u64 v[212:213], s[44:45], 0, v[184:185]
	s_mov_b32 m0, s69
	ds_read_b128 v[162:165], v230 offset:16384
	ds_read_b128 v[166:169], v230 offset:17408
	ds_read_b128 v[170:173], v230 offset:18432
	ds_read_b128 v[192:195], v230 offset:19456
	ds_read_b128 v[196:199], v230 offset:20480
	ds_read_b128 v[200:203], v230 offset:21504
	ds_read_b128 v[204:207], v230 offset:22528
	ds_read_b128 v[208:211], v230 offset:23552
	global_load_lds_dwordx4 v[212:213], off
	s_add_i32 m0, s69, 0x2000
	s_add_u32 s70, s44, 0x40000
	v_lshl_add_u64 v[214:215], s[44:45], 0, v[180:181]
	s_addc_u32 s71, s45, 0
	s_add_i32 s69, s72, s52
	global_load_lds_dwordx4 v[214:215], off
	v_lshl_add_u64 v[216:217], s[70:71], 0, v[184:185]
	s_mov_b32 m0, s69
	v_lshl_add_u64 v[218:219], s[46:47], 0, v[182:183]
	global_load_lds_dwordx4 v[216:217], off
	v_lshl_add_u64 v[216:217], s[70:71], 0, v[180:181]
	s_add_i32 m0, s69, 0x2000
	s_nop 0
	global_load_lds_dwordx4 v[216:217], off
	v_lshl_add_u64 v[216:217], s[46:47], 0, v[186:187]
	s_mov_b32 m0, s53
	s_nop 0
	global_load_lds_dwordx4 v[216:217], off
	s_mov_b32 m0, s54
	s_nop 0
	global_load_lds_dwordx4 v[218:219], off
	s_waitcnt vmcnt(8)
	s_waitcnt lgkmcnt(0)
	s_barrier
; #define PG8_STAGE(bufoff, gbase, voff) do { _Pragma("unroll") for (int _i = 0; _i < 2; ++_i) \
;         __builtin_amdgcn_global_load_lds((const unsigned*)((const char*)(gbase) + (voff)[_i]), (PG8_LAS unsigned*)(lds + (bufoff) + ldsw + _i * 8192), 16, 0, 0); } while (0)
; #define PG8_LDA(dst, b, h) do { _Pragma("unroll") for (int m = 0; m < 4; ++m) _Pragma("unroll") for (int k = 0; k < 2; ++k) dst[m][k] = *(const PG8_LAS bf16x8*)(lds + PG8_SA(b, h) + aoff + m * 2048 + k * 1024); } while (0)
; #define PG8_LDB(dst, b, h) do { _Pragma("unroll") for (int n = 0; n < 2; ++n) _Pragma("unroll") for (int k = 0; k < 2; ++k) dst[n][k] = *(const PG8_LAS bf16x8*)(lds + PG8_SB(b, h) + boff + n * 2048 + k * 1024); } while (0)
; #define PG8_MMA(ai, bj, At, Bt) do { __builtin_amdgcn_s_setprio(1); _Pragma("unroll") for (int m = 0; m < 4; ++m) _Pragma("unroll") for (int n = 0; n < 2; ++n) _Pragma("unroll") for (int k = 0; k < 2; ++k) \
;         acc[ai][bj][m][n] = __builtin_amdgcn_mfma_f32_16x16x32_bf16(Bt[n][k], At[m][k], acc[ai][bj][m][n], 0, 0, 0); __builtin_amdgcn_s_setprio(0); } while (0)
; #define PG8_WAIT_V(n) asm volatile("s_waitcnt vmcnt(" #n ")" ::: "memory")
; #define PG8_WAIT_L(n) asm volatile("s_waitcnt lgkmcnt(" #n ")" ::: "memory")
; #define PG8_BAR __builtin_amdgcn_s_barrier()
; #define PG8_SCHED __builtin_amdgcn_sched_barrier(0)
; template <class Epi, class Sched, bool ALIGN_EPI = false, bool SP2 = false>
; __device__ __forceinline__ void gemm_phase(PG8_LAS unsigned char* lds, const Gemm g, const Sched& S, const Epi& E) {
;     ...
;             PG8_WAIT_V(8); PG8_WAIT_L(0); PG8_BAR; PG8_MMA(1, 0, At, B0); PG8_MMA(1, 1, At, B1); PG8_BAR; PG8_SCHED;
;             PG8_LDB(B0, 1, 0); PG8_LDB(B1, 1, 1); PG8_SCHED; PG8_LDA(At, 1, 0); PG8_STAGE(PG8_SA(0, 1), a2 + hstep, voffA);
;             PG8_WAIT_V(8); PG8_WAIT_L(0); PG8_BAR; PG8_MMA(0, 0, At, B0); PG8_MMA(0, 1, At, B1); PG8_BAR; PG8_SCHED;
;             PG8_LDA(At, 1, 1); PG8_STAGE(PG8_SB(1, 0), b3, voffB); PG8_STAGE(PG8_SB(1, 1), b3 + hstep, voffB); PG8_STAGE(PG8_SA(1, 0), a3, voffA);
	s_setprio 1
	s_waitcnt lgkmcnt(0)
	v_mfma_f32_16x16x32_bf16 v[62:65], v[106:109], v[162:165], v[62:65]
	v_mfma_f32_16x16x32_bf16 v[58:61], v[114:117], v[162:165], v[58:61]
	v_mfma_f32_16x16x32_bf16 v[46:49], v[106:109], v[170:173], v[46:49]
	v_mfma_f32_16x16x32_bf16 v[42:45], v[114:117], v[170:173], v[42:45]
	v_mfma_f32_16x16x32_bf16 v[30:33], v[106:109], v[196:199], v[30:33]
	v_mfma_f32_16x16x32_bf16 v[26:29], v[114:117], v[196:199], v[26:29]
	v_mfma_f32_16x16x32_bf16 v[14:17], v[106:109], v[204:207], v[14:17]
	v_mfma_f32_16x16x32_bf16 v[10:13], v[114:117], v[204:207], v[10:13]
	v_mfma_f32_16x16x32_bf16 v[62:65], v[110:113], v[166:169], v[62:65]
	v_mfma_f32_16x16x32_bf16 v[58:61], v[118:121], v[166:169], v[58:61]
	v_mfma_f32_16x16x32_bf16 v[46:49], v[110:113], v[192:195], v[46:49]
	v_mfma_f32_16x16x32_bf16 v[42:45], v[118:121], v[192:195], v[42:45]
	v_mfma_f32_16x16x32_bf16 v[30:33], v[110:113], v[200:203], v[30:33]
	v_mfma_f32_16x16x32_bf16 v[26:29], v[118:121], v[200:203], v[26:29]
	v_mfma_f32_16x16x32_bf16 v[14:17], v[110:113], v[208:211], v[14:17]
	v_mfma_f32_16x16x32_bf16 v[10:13], v[118:121], v[208:211], v[10:13]
	s_setprio 0
	s_setprio 1
	v_mfma_f32_16x16x32_bf16 v[54:57], v[122:125], v[162:165], v[54:57]
	v_mfma_f32_16x16x32_bf16 v[50:53], v[130:133], v[162:165], v[50:53]
	v_mfma_f32_16x16x32_bf16 v[38:41], v[122:125], v[170:173], v[38:41]
	v_mfma_f32_16x16x32_bf16 v[34:37], v[130:133], v[170:173], v[34:37]
	v_mfma_f32_16x16x32_bf16 v[22:25], v[122:125], v[196:199], v[22:25]
	v_mfma_f32_16x16x32_bf16 v[18:21], v[130:133], v[196:199], v[18:21]
	v_mfma_f32_16x16x32_bf16 v[6:9], v[122:125], v[204:207], v[6:9]
	v_mfma_f32_16x16x32_bf16 v[2:5], v[130:133], v[204:207], v[2:5]
	v_mfma_f32_16x16x32_bf16 v[54:57], v[126:129], v[166:169], v[54:57]
	v_mfma_f32_16x16x32_bf16 v[50:53], v[134:137], v[166:169], v[50:53]
	v_mfma_f32_16x16x32_bf16 v[38:41], v[126:129], v[192:195], v[38:41]
	v_mfma_f32_16x16x32_bf16 v[34:37], v[134:137], v[192:195], v[34:37]
	v_mfma_f32_16x16x32_bf16 v[22:25], v[126:129], v[200:203], v[22:25]
	v_mfma_f32_16x16x32_bf16 v[18:21], v[134:137], v[200:203], v[18:21]
	v_mfma_f32_16x16x32_bf16 v[6:9], v[126:129], v[208:211], v[6:9]
	v_mfma_f32_16x16x32_bf16 v[2:5], v[134:137], v[208:211], v[2:5]
	s_setprio 0
	s_barrier
	s_add_i32 s69, 0, 0x18000
	s_add_i32 s70, 0, 0x1c000
	v_add_u32_e32 v118, s69, v229
	v_add_u32_e32 v134, s70, v229
	ds_read_b128 v[106:109], v118
	ds_read_b128 v[110:113], v118 offset:1024
	ds_read_b128 v[114:117], v118 offset:2048
	ds_read_b128 v[118:121], v118 offset:3072
	ds_read_b128 v[122:125], v134
	ds_read_b128 v[126:129], v134 offset:1024
	ds_read_b128 v[130:133], v134 offset:2048
	ds_read_b128 v[134:137], v134 offset:3072
	ds_read_b128 v[162:165], v230 offset:32768
	ds_read_b128 v[166:169], v230 offset:33792
	ds_read_b128 v[170:173], v230 offset:34816
	ds_read_b128 v[192:195], v230 offset:35840
	ds_read_b128 v[196:199], v230 offset:36864
	ds_read_b128 v[200:203], v230 offset:37888
	ds_read_b128 v[204:207], v230 offset:38912
	ds_read_b128 v[208:211], v230 offset:39936
	s_waitcnt vmcnt(6)
	s_waitcnt lgkmcnt(0)
	s_barrier
	s_setprio 1
	s_waitcnt lgkmcnt(0)
	v_mfma_f32_16x16x32_bf16 v[158:161], v[106:109], v[162:165], v[158:161]
	v_mfma_f32_16x16x32_bf16 v[154:157], v[114:117], v[162:165], v[154:157]
	v_mfma_f32_16x16x32_bf16 v[142:145], v[106:109], v[170:173], v[142:145]
	v_mfma_f32_16x16x32_bf16 v[138:141], v[114:117], v[170:173], v[138:141]
	v_mfma_f32_16x16x32_bf16 v[94:97], v[106:109], v[196:199], v[94:97]
	v_mfma_f32_16x16x32_bf16 v[90:93], v[114:117], v[196:199], v[90:93]
	v_mfma_f32_16x16x32_bf16 v[78:81], v[106:109], v[204:207], v[78:81]
	v_mfma_f32_16x16x32_bf16 v[74:77], v[114:117], v[204:207], v[74:77]
	v_mfma_f32_16x16x32_bf16 v[158:161], v[110:113], v[166:169], v[158:161]
	v_mfma_f32_16x16x32_bf16 v[154:157], v[118:121], v[166:169], v[154:157]
	v_mfma_f32_16x16x32_bf16 v[142:145], v[110:113], v[192:195], v[142:145]
	v_mfma_f32_16x16x32_bf16 v[138:141], v[118:121], v[192:195], v[138:141]
	v_mfma_f32_16x16x32_bf16 v[94:97], v[110:113], v[200:203], v[94:97]
	v_mfma_f32_16x16x32_bf16 v[90:93], v[118:121], v[200:203], v[90:93]
	v_mfma_f32_16x16x32_bf16 v[78:81], v[110:113], v[208:211], v[78:81]
	v_mfma_f32_16x16x32_bf16 v[74:77], v[118:121], v[208:211], v[74:77]
	s_setprio 0
	s_setprio 1
	v_mfma_f32_16x16x32_bf16 v[150:153], v[122:125], v[162:165], v[150:153]
	v_mfma_f32_16x16x32_bf16 v[146:149], v[130:133], v[162:165], v[146:149]
	v_mfma_f32_16x16x32_bf16 v[102:105], v[122:125], v[170:173], v[102:105]
	v_mfma_f32_16x16x32_bf16 v[98:101], v[130:133], v[170:173], v[98:101]
	v_mfma_f32_16x16x32_bf16 v[86:89], v[122:125], v[196:199], v[86:89]
	v_mfma_f32_16x16x32_bf16 v[82:85], v[130:133], v[196:199], v[82:85]
	v_mfma_f32_16x16x32_bf16 v[70:73], v[122:125], v[204:207], v[70:73]
	v_mfma_f32_16x16x32_bf16 v[66:69], v[130:133], v[204:207], v[66:69]
	v_mfma_f32_16x16x32_bf16 v[150:153], v[126:129], v[166:169], v[150:153]
	v_mfma_f32_16x16x32_bf16 v[146:149], v[134:137], v[166:169], v[146:149]
	v_mfma_f32_16x16x32_bf16 v[102:105], v[126:129], v[192:195], v[102:105]
	v_mfma_f32_16x16x32_bf16 v[98:101], v[134:137], v[192:195], v[98:101]
	v_mfma_f32_16x16x32_bf16 v[86:89], v[126:129], v[200:203], v[86:89]
	v_mfma_f32_16x16x32_bf16 v[82:85], v[134:137], v[200:203], v[82:85]
	v_mfma_f32_16x16x32_bf16 v[70:73], v[126:129], v[208:211], v[70:73]
	v_mfma_f32_16x16x32_bf16 v[66:69], v[134:137], v[208:211], v[66:69]
	s_setprio 0
	s_barrier
; #define PG8_STAGE(bufoff, gbase, voff) do { _Pragma("unroll") for (int _i = 0; _i < 2; ++_i) \
;         __builtin_amdgcn_global_load_lds((const unsigned*)((const char*)(gbase) + (voff)[_i]), (PG8_LAS unsigned*)(lds + (bufoff) + ldsw + _i * 8192), 16, 0, 0); } while (0)
; #define PG8_LDA(dst, b, h) do { _Pragma("unroll") for (int m = 0; m < 4; ++m) _Pragma("unroll") for (int k = 0; k < 2; ++k) dst[m][k] = *(const PG8_LAS bf16x8*)(lds + PG8_SA(b, h) + aoff + m * 2048 + k * 1024); } while (0)
; #define PG8_LDB(dst, b, h) do { _Pragma("unroll") for (int n = 0; n < 2; ++n) _Pragma("unroll") for (int k = 0; k < 2; ++k) dst[n][k] = *(const PG8_LAS bf16x8*)(lds + PG8_SB(b, h) + boff + n * 2048 + k * 1024); } while (0)
; template <class Epi, class Sched, bool ALIGN_EPI = false, bool SP2 = false>
; __device__ __forceinline__ void gemm_phase(PG8_LAS unsigned char* lds, const Gemm g, const Sched& S, const Epi& E) {
;     ...
;         for (int t = 0; t < nt; t += 2) {
;             const bool last = (t == nt - 2);
;             const char* a1 = cA + (size_t)(t + 1) * kstep;
;             const char* a2 = last ? nA : cA + (size_t)(t + 2) * kstep; const char* b2 = last ? nB : cB + (size_t)(t + 2) * kstep;
;             const char* a3 = a2 + kstep; const char* b3 = b2 + kstep;
;             if (last && has_next) S.a_ready(nxt);
;             if constexpr (SP2) {
;             PG8_LDB(B0, 0, 0); PG8_LDB(B1, 0, 1); PG8_SCHED; PG8_LDA(At, 0, 0); PG8_STAGE(PG8_SA(1, 1), a1 + hstep, voffA);
;             PG8_WAIT_V(8); PG8_WAIT_L(0); PG8_BAR; PG8_MMA(0, 0, At, B0); PG8_MMA(0, 1, At, B1); PG8_BAR; PG8_SCHED;
;             PG8_LDA(At, 0, 1); PG8_STAGE(PG8_SB(0, 0), b2, voffB); PG8_STAGE(PG8_SB(0, 1), b2 + hstep, voffB); PG8_STAGE(PG8_SA(0, 0), a2, voffA);
;             PG8_WAIT_V(8); PG8_WAIT_L(0); PG8_BAR; PG8_MMA(1, 0, At, B0); PG8_MMA(1, 1, At, B1); PG8_BAR; PG8_SCHED;
;             PG8_LDB(B0, 1, 0); PG8_LDB(B1, 1, 1); PG8_SCHED; PG8_LDA(At, 1, 0); PG8_STAGE(PG8_SA(0, 1), a2 + hstep, voffA);
;             PG8_WAIT_V(8); PG8_WAIT_L(0); PG8_BAR; PG8_MMA(0, 0, At, B0); PG8_MMA(0, 1, At, B1); PG8_BAR; PG8_SCHED;
;             PG8_LDA(At, 1, 1); PG8_STAGE(PG8_SB(1, 0), b3, voffB); PG8_STAGE(PG8_SB(1, 1), b3 + hstep, voffB); PG8_STAGE(PG8_SA(1, 0), a3, voffA);
;             PG8_WAIT_V(8); PG8_WAIT_L(0); PG8_BAR; PG8_MMA(1, 0, At, B0); PG8_MMA(1, 1, At, B1); PG8_BAR; PG8_SCHED;
	s_add_u32 s46, s46, 0x40000
	s_addc_u32 s47, s47, 0
	s_mov_b32 m0, s55
	v_lshl_add_u64 v[220:221], s[46:47], 0, v[186:187]
	global_load_lds_dwordx4 v[220:221], off
	v_lshl_add_u64 v[220:221], s[46:47], 0, v[182:183]
	s_mov_b32 m0, s56
	s_nop 0
	global_load_lds_dwordx4 v[220:221], off
	s_add_i32 s46, s69, s52
	v_lshl_add_u64 v[212:213], v[212:213], 0, s[96:97]
	s_mov_b32 m0, s46
	ds_read_b128 v[162:165], v230 offset:49152
	ds_read_b128 v[166:169], v230 offset:50176
	ds_read_b128 v[170:173], v230 offset:51200
	ds_read_b128 v[192:195], v230 offset:52224
	ds_read_b128 v[196:199], v230 offset:53248
	ds_read_b128 v[200:203], v230 offset:54272
	ds_read_b128 v[204:207], v230 offset:55296
	ds_read_b128 v[208:211], v230 offset:56320
	global_load_lds_dwordx4 v[212:213], off
	s_add_i32 m0, s46, 0x2000
	s_add_u32 s44, s44, 0x40080
	v_lshl_add_u64 v[212:213], v[214:215], 0, s[96:97]
	s_addc_u32 s45, s45, 0
	s_add_i32 s46, s70, s52
	global_load_lds_dwordx4 v[212:213], off
	v_lshl_add_u64 v[212:213], s[44:45], 0, v[184:185]
	s_mov_b32 m0, s46
	s_nop 0
	global_load_lds_dwordx4 v[212:213], off
	v_lshl_add_u64 v[212:213], s[44:45], 0, v[180:181]
	s_add_i32 m0, s46, 0x2000
	s_nop 0
	global_load_lds_dwordx4 v[212:213], off
	v_lshl_add_u64 v[212:213], v[216:217], 0, s[96:97]
	s_mov_b32 m0, s60
	s_nop 0
	global_load_lds_dwordx4 v[212:213], off
	v_lshl_add_u64 v[212:213], v[218:219], 0, s[96:97]
	s_mov_b32 m0, s61
	s_nop 0
	global_load_lds_dwordx4 v[212:213], off
	s_waitcnt vmcnt(8)
	s_waitcnt lgkmcnt(0)
	s_barrier
	s_setprio 1
	s_waitcnt lgkmcnt(0)
	v_mfma_f32_16x16x32_bf16 v[62:65], v[106:109], v[162:165], v[62:65]
	v_mfma_f32_16x16x32_bf16 v[58:61], v[114:117], v[162:165], v[58:61]
	v_mfma_f32_16x16x32_bf16 v[46:49], v[106:109], v[170:173], v[46:49]
	v_mfma_f32_16x16x32_bf16 v[42:45], v[114:117], v[170:173], v[42:45]
	v_mfma_f32_16x16x32_bf16 v[30:33], v[106:109], v[196:199], v[30:33]
	v_mfma_f32_16x16x32_bf16 v[26:29], v[114:117], v[196:199], v[26:29]
	v_mfma_f32_16x16x32_bf16 v[14:17], v[106:109], v[204:207], v[14:17]
	v_mfma_f32_16x16x32_bf16 v[10:13], v[114:117], v[204:207], v[10:13]
	v_mfma_f32_16x16x32_bf16 v[62:65], v[110:113], v[166:169], v[62:65]
	v_mfma_f32_16x16x32_bf16 v[58:61], v[118:121], v[166:169], v[58:61]
	v_mfma_f32_16x16x32_bf16 v[46:49], v[110:113], v[192:195], v[46:49]
	v_mfma_f32_16x16x32_bf16 v[42:45], v[118:121], v[192:195], v[42:45]
	v_mfma_f32_16x16x32_bf16 v[30:33], v[110:113], v[200:203], v[30:33]
	v_mfma_f32_16x16x32_bf16 v[26:29], v[118:121], v[200:203], v[26:29]
	v_mfma_f32_16x16x32_bf16 v[14:17], v[110:113], v[208:211], v[14:17]
	v_mfma_f32_16x16x32_bf16 v[10:13], v[118:121], v[208:211], v[10:13]
	s_setprio 0
	s_setprio 1
	v_mfma_f32_16x16x32_bf16 v[54:57], v[122:125], v[162:165], v[54:57]
	v_mfma_f32_16x16x32_bf16 v[50:53], v[130:133], v[162:165], v[50:53]
	v_mfma_f32_16x16x32_bf16 v[38:41], v[122:125], v[170:173], v[38:41]
	v_mfma_f32_16x16x32_bf16 v[34:37], v[130:133], v[170:173], v[34:37]
	v_mfma_f32_16x16x32_bf16 v[22:25], v[122:125], v[196:199], v[22:25]
	v_mfma_f32_16x16x32_bf16 v[18:21], v[130:133], v[196:199], v[18:21]
	v_mfma_f32_16x16x32_bf16 v[6:9], v[122:125], v[204:207], v[6:9]
	v_mfma_f32_16x16x32_bf16 v[2:5], v[130:133], v[204:207], v[2:5]
	v_mfma_f32_16x16x32_bf16 v[54:57], v[126:129], v[166:169], v[54:57]
	v_mfma_f32_16x16x32_bf16 v[50:53], v[134:137], v[166:169], v[50:53]
	v_mfma_f32_16x16x32_bf16 v[38:41], v[126:129], v[192:195], v[38:41]
	v_mfma_f32_16x16x32_bf16 v[34:37], v[134:137], v[192:195], v[34:37]
	v_mfma_f32_16x16x32_bf16 v[22:25], v[126:129], v[200:203], v[22:25]
	v_mfma_f32_16x16x32_bf16 v[18:21], v[134:137], v[200:203], v[18:21]
	v_mfma_f32_16x16x32_bf16 v[6:9], v[126:129], v[208:211], v[6:9]
	v_mfma_f32_16x16x32_bf16 v[2:5], v[134:137], v[208:211], v[2:5]
	s_setprio 0
	s_barrier
	s_add_i32 s68, s68, 2
	s_add_u32 s8, s8, 0x100
	s_addc_u32 s9, s9, 0
	s_add_u32 s66, s66, 0x100
	s_addc_u32 s67, s67, 0
	s_cmp_gt_u32 s68, 13
	s_cbranch_scc0 .LBB0_1247
	s_and_b64 vcc, exec, s[24:25]
	s_cbranch_vccz .LBB0_1250
	s_barrier
